# E64: prompt-FoX QK block - one lgkmcnt wait per 4-MFMA group (9 fewer s_waitcnt per tile) on top of E63
# baseline (speedup 1.0000x reference)
.LBB0_1390:
	s_cmp_le_i32 s16, s15
	s_cselect_b64 s[20:21], -1, 0
	s_and_b64 s[20:21], s[84:85], s[20:21]
	s_andn2_b64 vcc, exec, s[20:21]
	s_cbranch_vccnz .LBB0_1396
	s_bitcmp1_b32 s18, 0
	s_cselect_b32 s18, 0xa800, 0
	s_add_i32 s70, s18, 0
	ds_read_b128 v[82:85], v198
	ds_read_b128 v[86:89], v198 offset:32
	ds_read_b128 v[90:93], v198 offset:64
	ds_read_b128 v[94:97], v198 offset:96
	v_add3_u32 v2, s70, v214, v186
	ds_read_b128 v[226:229], v2
	ds_read_b128 v[230:233], v2 offset:32
	ds_read_b128 v[234:237], v2 offset:64
	ds_read_b128 v[238:241], v2 offset:96
	ds_read_b128 v[50:53], v198 offset:128
	ds_read_b128 v[54:57], v198 offset:160
	ds_read_b128 v[58:61], v198 offset:192
	ds_read_b128 v[62:65], v198 offset:224
	s_add_i32 s18, s16, 0x7f
	s_cmp_le_i32 s18, s13
	s_waitcnt lgkmcnt(4)
	v_mfma_f32_32x32x16_bf16 v[82:97], v[226:229], v[114:117], v[82:97]
	ds_read_b128 v[4:7], v2 offset:4608
	v_mfma_f32_32x32x16_bf16 v[82:97], v[230:233], v[118:121], v[82:97]
	ds_read_b128 v[8:11], v2 offset:4640
	v_mfma_f32_32x32x16_bf16 v[82:97], v[234:237], v[122:125], v[82:97]
	ds_read_b128 v[12:15], v2 offset:4672
	v_mfma_f32_32x32x16_bf16 v[82:97], v[238:241], v[126:129], v[82:97]
	ds_read_b128 v[160:163], v2 offset:4704
	ds_read_b128 v[66:69], v198 offset:256
	ds_read_b128 v[70:73], v198 offset:288
	ds_read_b128 v[74:77], v198 offset:320
	ds_read_b128 v[78:81], v198 offset:352
	s_waitcnt lgkmcnt(4)
	v_mfma_f32_32x32x16_bf16 v[50:65], v[4:7], v[114:117], v[50:65]
	ds_read_b128 v[226:229], v2 offset:9216
	v_mfma_f32_32x32x16_bf16 v[50:65], v[8:11], v[118:121], v[50:65]
	ds_read_b128 v[230:233], v2 offset:9248
	v_mfma_f32_32x32x16_bf16 v[50:65], v[12:15], v[122:125], v[50:65]
	ds_read_b128 v[234:237], v2 offset:9280
	v_mfma_f32_32x32x16_bf16 v[50:65], v[160:163], v[126:129], v[50:65]
	ds_read_b128 v[238:241], v2 offset:9312
	ds_read_b128 v[98:101], v198 offset:384
	ds_read_b128 v[102:105], v198 offset:416
	ds_read_b128 v[106:109], v198 offset:448
	ds_read_b128 v[110:113], v198 offset:480
	s_waitcnt lgkmcnt(4)
	v_mfma_f32_32x32x16_bf16 v[66:81], v[226:229], v[114:117], v[66:81]
	ds_read_b128 v[4:7], v2 offset:13824
	v_mfma_f32_32x32x16_bf16 v[66:81], v[230:233], v[118:121], v[66:81]
	ds_read_b128 v[8:11], v2 offset:13856
	v_mfma_f32_32x32x16_bf16 v[66:81], v[234:237], v[122:125], v[66:81]
	ds_read_b128 v[12:15], v2 offset:13888
	v_mfma_f32_32x32x16_bf16 v[66:81], v[238:241], v[126:129], v[66:81]
	ds_read_b128 v[160:163], v2 offset:13920
	s_waitcnt lgkmcnt(3)
	v_mfma_f32_32x32x16_bf16 v[98:113], v[4:7], v[114:117], v[98:113]
	s_waitcnt lgkmcnt(2)
	v_mfma_f32_32x32x16_bf16 v[98:113], v[8:11], v[118:121], v[98:113]
	s_waitcnt lgkmcnt(1)
	v_mfma_f32_32x32x16_bf16 v[98:113], v[12:15], v[122:125], v[98:113]
	s_waitcnt lgkmcnt(0)
	v_mfma_f32_32x32x16_bf16 v[98:113], v[160:163], v[126:129], v[98:113]
	s_cbranch_scc1 .LBB0_1393
	v_cmp_gt_i32_e64 s[46:47], 26, v195
	v_cmp_gt_i32_e64 s[48:49], 27, v195
	v_cmp_gt_i32_e64 s[44:45], 25, v195
	s_and_b64 s[46:47], s[48:49], s[46:47]
	v_cmp_gt_i32_e64 s[42:43], 24, v195
	v_cndmask_b32_e64 v97, v97, v190, s[48:49]
	v_cndmask_b32_e64 v96, v96, v190, s[46:47]
	s_and_b64 s[44:45], s[46:47], s[44:45]
	v_cmp_gt_i32_e64 s[46:47], 58, v195
	v_cmp_gt_i32_e64 s[48:49], 59, v195
	v_cmp_gt_i32_e64 s[40:41], 19, v195
	v_cndmask_b32_e64 v95, v95, v190, s[44:45]
	s_and_b64 s[42:43], s[44:45], s[42:43]
	v_cmp_gt_i32_e64 s[44:45], 57, v195
	s_and_b64 s[46:47], s[48:49], s[46:47]
	v_cmp_gt_i32_e64 s[38:39], 18, v195
	v_cndmask_b32_e64 v94, v94, v190, s[42:43]
	s_and_b64 s[40:41], s[42:43], s[40:41]
	v_cmp_gt_i32_e64 s[42:43], 56, v195
	v_cndmask_b32_e64 v65, v65, v190, s[48:49]
	v_cndmask_b32_e64 v64, v64, v190, s[46:47]
	s_and_b64 s[44:45], s[46:47], s[44:45]
	s_movk_i32 s46, 0x5a
	s_movk_i32 s48, 0x5b
	v_cmp_gt_i32_e64 s[36:37], 17, v195
	v_cndmask_b32_e64 v93, v93, v190, s[40:41]
	s_and_b64 s[38:39], s[40:41], s[38:39]
	v_cmp_gt_i32_e64 s[40:41], 51, v195
	v_cndmask_b32_e64 v63, v63, v190, s[44:45]
	s_and_b64 s[42:43], s[44:45], s[42:43]
	s_movk_i32 s44, 0x59
	v_cmp_gt_i32_e64 s[46:47], s46, v195
	v_cmp_gt_i32_e64 s[48:49], s48, v195
	v_cmp_gt_i32_e64 s[34:35], 16, v195
	v_cndmask_b32_e64 v92, v92, v190, s[38:39]
	s_and_b64 s[36:37], s[38:39], s[36:37]
	v_cmp_gt_i32_e64 s[38:39], 50, v195
	v_cndmask_b32_e64 v62, v62, v190, s[42:43]
	s_and_b64 s[40:41], s[42:43], s[40:41]
	s_movk_i32 s42, 0x58
	v_cmp_gt_i32_e64 s[44:45], s44, v195
	s_and_b64 s[46:47], s[48:49], s[46:47]
	v_cmp_gt_i32_e64 s[30:31], 11, v195
	v_cndmask_b32_e64 v91, v91, v190, s[36:37]
	s_and_b64 s[34:35], s[36:37], s[34:35]
	v_cmp_gt_i32_e64 s[36:37], 49, v195
	v_cndmask_b32_e64 v61, v61, v190, s[40:41]
	s_and_b64 s[38:39], s[40:41], s[38:39]
	s_movk_i32 s40, 0x53
	v_cmp_gt_i32_e64 s[42:43], s42, v195
	s_and_b64 s[44:45], s[46:47], s[44:45]
	v_cmp_gt_i32_e64 s[28:29], 10, v195
	v_cndmask_b32_e64 v90, v90, v190, s[34:35]
	s_and_b64 s[30:31], s[34:35], s[30:31]
	v_cmp_gt_i32_e64 s[34:35], 48, v195
	v_cndmask_b32_e64 v60, v60, v190, s[38:39]
	s_and_b64 s[36:37], s[38:39], s[36:37]
	s_movk_i32 s38, 0x52
	v_cmp_gt_i32_e64 s[40:41], s40, v195
	v_cndmask_b32_e64 v81, v81, v190, s[48:49]
	v_cndmask_b32_e64 v80, v80, v190, s[46:47]
	s_and_b64 s[42:43], s[44:45], s[42:43]
	s_movk_i32 s46, 0x7a
	s_movk_i32 s48, 0x7b
	v_cmp_gt_i32_e64 s[26:27], 9, v195
	v_cndmask_b32_e64 v89, v89, v190, s[30:31]
	s_and_b64 s[28:29], s[30:31], s[28:29]
	v_cmp_gt_i32_e64 s[30:31], 43, v195
	v_cndmask_b32_e64 v59, v59, v190, s[36:37]
	s_and_b64 s[34:35], s[36:37], s[34:35]
	s_movk_i32 s36, 0x51
	v_cmp_gt_i32_e64 s[38:39], s38, v195
	v_cndmask_b32_e64 v79, v79, v190, s[44:45]
	s_and_b64 s[40:41], s[42:43], s[40:41]
	s_movk_i32 s44, 0x79
	v_cmp_gt_i32_e64 s[46:47], s46, v195
	v_cmp_gt_i32_e64 s[48:49], s48, v195
	v_cmp_gt_i32_e64 s[24:25], 8, v195
	v_cndmask_b32_e64 v88, v88, v190, s[28:29]
	s_and_b64 s[26:27], s[28:29], s[26:27]
	v_cmp_gt_i32_e64 s[28:29], 42, v195
	v_cndmask_b32_e64 v58, v58, v190, s[34:35]
	s_and_b64 s[30:31], s[34:35], s[30:31]
	s_movk_i32 s34, 0x50
	v_cmp_gt_i32_e64 s[36:37], s36, v195
	v_cndmask_b32_e64 v78, v78, v190, s[42:43]
	s_and_b64 s[38:39], s[40:41], s[38:39]
	s_movk_i32 s42, 0x78
	v_cmp_gt_i32_e64 s[44:45], s44, v195
	s_and_b64 s[46:47], s[48:49], s[46:47]
	v_cmp_gt_i32_e64 s[22:23], 3, v195
	v_cndmask_b32_e64 v87, v87, v190, s[26:27]
	s_and_b64 s[24:25], s[26:27], s[24:25]
	v_cmp_gt_i32_e64 s[26:27], 41, v195
	v_cndmask_b32_e64 v57, v57, v190, s[30:31]
	s_and_b64 s[28:29], s[30:31], s[28:29]
	s_movk_i32 s30, 0x4b
	v_cmp_gt_i32_e64 s[34:35], s34, v195
	v_cndmask_b32_e64 v77, v77, v190, s[40:41]
	s_and_b64 s[36:37], s[38:39], s[36:37]
	s_movk_i32 s40, 0x73
	v_cmp_gt_i32_e64 s[42:43], s42, v195
	s_and_b64 s[44:45], s[46:47], s[44:45]
	v_cmp_gt_i32_e64 s[20:21], 2, v195
	v_cndmask_b32_e64 v86, v86, v190, s[24:25]
	s_and_b64 s[22:23], s[24:25], s[22:23]
	v_cmp_gt_i32_e64 s[24:25], 40, v195
	v_cndmask_b32_e64 v56, v56, v190, s[28:29]
	s_and_b64 s[26:27], s[28:29], s[26:27]
	s_movk_i32 s28, 0x4a
	v_cmp_gt_i32_e64 s[30:31], s30, v195
	v_cndmask_b32_e64 v76, v76, v190, s[38:39]
	s_and_b64 s[34:35], s[36:37], s[34:35]
	s_movk_i32 s38, 0x72
	v_cmp_gt_i32_e64 s[40:41], s40, v195
	s_and_b64 s[42:43], s[44:45], s[42:43]
	v_cmp_gt_i32_e64 s[18:19], 1, v195
	v_cndmask_b32_e64 v85, v85, v190, s[22:23]
	s_and_b64 s[20:21], s[22:23], s[20:21]
	v_cmp_gt_i32_e64 s[22:23], 35, v195
	v_cndmask_b32_e64 v55, v55, v190, s[26:27]
	s_and_b64 s[24:25], s[26:27], s[24:25]
	s_movk_i32 s26, 0x49
	v_cmp_gt_i32_e64 s[28:29], s28, v195
	v_cndmask_b32_e64 v75, v75, v190, s[36:37]
	s_and_b64 s[30:31], s[34:35], s[30:31]
	s_movk_i32 s36, 0x71
	v_cmp_gt_i32_e64 s[38:39], s38, v195
	s_and_b64 s[40:41], s[42:43], s[40:41]
	v_cmp_gt_i32_e32 vcc, 0, v195
	v_cndmask_b32_e64 v84, v84, v190, s[20:21]
	s_and_b64 s[18:19], s[20:21], s[18:19]
	v_cmp_gt_i32_e64 s[20:21], 34, v195
	v_cndmask_b32_e64 v54, v54, v190, s[24:25]
	s_and_b64 s[22:23], s[24:25], s[22:23]
	s_movk_i32 s24, 0x48
	v_cmp_gt_i32_e64 s[26:27], s26, v195
	v_cndmask_b32_e64 v74, v74, v190, s[34:35]
	s_and_b64 s[28:29], s[30:31], s[28:29]
	s_movk_i32 s34, 0x70
	v_cmp_gt_i32_e64 s[36:37], s36, v195
	s_and_b64 s[38:39], s[40:41], s[38:39]
	v_cndmask_b32_e64 v83, v83, v190, s[18:19]
	s_and_b64 vcc, s[18:19], vcc
	v_cmp_gt_i32_e64 s[18:19], 33, v195
	v_cndmask_b32_e64 v53, v53, v190, s[22:23]
	s_and_b64 s[20:21], s[22:23], s[20:21]
	s_movk_i32 s22, 0x43
	v_cmp_gt_i32_e64 s[24:25], s24, v195
	v_cndmask_b32_e64 v73, v73, v190, s[30:31]
	s_and_b64 s[26:27], s[28:29], s[26:27]
	s_movk_i32 s30, 0x6b
	v_cmp_gt_i32_e64 s[34:35], s34, v195
	s_and_b64 s[36:37], s[38:39], s[36:37]
	v_cndmask_b32_e32 v82, v82, v190, vcc
	v_cmp_gt_i32_e32 vcc, 32, v195
	v_cndmask_b32_e64 v52, v52, v190, s[20:21]
	s_and_b64 s[18:19], s[20:21], s[18:19]
	s_movk_i32 s20, 0x42
	v_cmp_gt_i32_e64 s[22:23], s22, v195
	v_cndmask_b32_e64 v72, v72, v190, s[28:29]
	s_and_b64 s[24:25], s[26:27], s[24:25]
	s_movk_i32 s28, 0x6a
	v_cmp_gt_i32_e64 s[30:31], s30, v195
	s_and_b64 s[34:35], s[36:37], s[34:35]
	v_cndmask_b32_e64 v51, v51, v190, s[18:19]
	s_and_b64 vcc, s[18:19], vcc
	s_movk_i32 s18, 0x41
	v_cmp_gt_i32_e64 s[20:21], s20, v195
	v_cndmask_b32_e64 v71, v71, v190, s[26:27]
	s_and_b64 s[22:23], s[24:25], s[22:23]
	s_movk_i32 s26, 0x69
	v_cmp_gt_i32_e64 s[28:29], s28, v195
	s_and_b64 s[30:31], s[34:35], s[30:31]
	v_cmp_gt_i32_e64 s[18:19], s18, v195
	v_cndmask_b32_e64 v70, v70, v190, s[24:25]
	s_and_b64 s[20:21], s[22:23], s[20:21]
	s_movk_i32 s24, 0x68
	v_cmp_gt_i32_e64 s[26:27], s26, v195
	s_and_b64 s[28:29], s[30:31], s[28:29]
	v_cndmask_b32_e32 v50, v50, v190, vcc
	v_cmp_gt_i32_e32 vcc, 64, v195
	v_cndmask_b32_e64 v69, v69, v190, s[22:23]
	s_and_b64 s[18:19], s[20:21], s[18:19]
	s_movk_i32 s22, 0x63
	v_cmp_gt_i32_e64 s[24:25], s24, v195
	s_and_b64 s[26:27], s[28:29], s[26:27]
	v_cndmask_b32_e64 v68, v68, v190, s[20:21]
	v_cndmask_b32_e64 v67, v67, v190, s[18:19]
	s_and_b64 vcc, s[18:19], vcc
	s_movk_i32 s18, 0x60
	s_movk_i32 s20, 0x62
	v_cmp_gt_i32_e64 s[22:23], s22, v195
	s_and_b64 s[24:25], s[26:27], s[24:25]
	v_cndmask_b32_e32 v66, v66, v190, vcc
	v_cmp_gt_i32_e32 vcc, s18, v195
	s_movk_i32 s18, 0x61
	v_cmp_gt_i32_e64 s[20:21], s20, v195
	s_and_b64 s[22:23], s[24:25], s[22:23]
	v_cmp_gt_i32_e64 s[18:19], s18, v195
	s_and_b64 s[20:21], s[22:23], s[20:21]
	s_and_b64 s[18:19], s[20:21], s[18:19]
	s_and_b64 vcc, s[18:19], vcc
	v_cndmask_b32_e64 v113, v113, v190, s[48:49]
	v_cndmask_b32_e64 v112, v112, v190, s[46:47]
	v_cndmask_b32_e64 v111, v111, v190, s[44:45]
	v_cndmask_b32_e64 v110, v110, v190, s[42:43]
	v_cndmask_b32_e64 v109, v109, v190, s[40:41]
	v_cndmask_b32_e64 v108, v108, v190, s[38:39]
	v_cndmask_b32_e64 v107, v107, v190, s[36:37]
	v_cndmask_b32_e64 v106, v106, v190, s[34:35]
	v_cndmask_b32_e64 v105, v105, v190, s[30:31]
	v_cndmask_b32_e64 v104, v104, v190, s[28:29]
	v_cndmask_b32_e64 v103, v103, v190, s[26:27]
	v_cndmask_b32_e64 v102, v102, v190, s[24:25]
	v_cndmask_b32_e64 v101, v101, v190, s[22:23]
	v_cndmask_b32_e64 v100, v100, v190, s[20:21]
	v_cndmask_b32_e64 v99, v99, v190, s[18:19]
	v_cndmask_b32_e32 v98, v98, v190, vcc
